# hyena: 16 adjacent channel pairs per workgroup + in-phase transpose of own G block; separate transpose phase skipped
# baseline (speedup 1.0000x reference)
; #define LAS __attribute__((address_space(3)))
; __device__ __forceinline__ void fft_tables(LAS cf* Thi, LAS cf* Tlo, int tid) {
;     if (tid < 256) { const int aidx = tid & 127; const float ang = (tid < 128) ? (-6.283185307179586f * (float)aidx / 128.0f) : (-6.283185307179586f * (float)aidx / 16384.0f);
;         float s, c; sincosf(ang, &s, &c); if (tid < 128) Thi[aidx] = (cf){c, s}; else Tlo[aidx] = (cf){c, s}; }
;     __syncthreads();
; }
; __device__ __forceinline__ void hyena_phase(LAS unsigned char* L, const Args& a, int vcu, int G) {
;     const int tid = threadIdx.x;
;     LAS cf* z = (LAS cf*)L; LAS cf* Thi = (LAS cf*)(L + 131072); LAS cf* Tlo = Thi + 128;
;     const bf16_t* ZT = (const bf16_t*)(a.ws + WS_ZT); bf16_t* Gc = (bf16_t*)(a.ws + WS_G);
;     const f32x4* SD = (const f32x4*)(a.ws + WS_SD); const f32x4* SD8 = (const f32x4*)(a.ws + WS_SD8);
;     const float* cw = a.in[15]; const float* cb = a.in[16]; const float* skip = a.in[25];
;     fft_tables(Thi, Tlo, tid);
;     Raw8 nx1a[2], nx1b[2], nxva[2], nxvb[2];
;     ...
;     if (vcu < 4096) HY_PREFETCH(vcu);
;     for (int unit = vcu; unit < 4096; unit += G) {
;         const int b = unit & 7, pair = unit >> 3, ca = 2 * pair;
.LBB0_988:
	s_cmp_lt_i32 s30, 12
	s_cselect_b64 s[4:5], -1, 0
	s_and_b64 s[12:13], s[4:5], s[0:1]
	s_andn2_b64 vcc, exec, s[12:13]
	s_cbranch_vccnz .LBB0_1087
	s_lshr_b32 s74, s96, 3
	s_and_b32 s96, s96, 7
	s_lshl_b32 s74, s74, 7
	s_add_i32 s96, s96, s74
	s_add_i32 s75, s96, 0x80
	s_movk_i32 s0, 0x100
	v_cmp_gt_u32_e32 vcc, s0, v152
	v_and_b32_e32 v48, 0x7f, v152
	s_and_saveexec_b64 s[8:9], vcc
	s_cbranch_execz .LBB0_991
	s_movk_i32 s0, 0x80
	s_add_i32 s1, 0, 0x20000
	s_add_i32 s4, 0, 0x20400
	v_mov_b32_e32 v0, s4
	v_mov_b32_e32 v1, s1
	v_cmp_gt_u32_e32 vcc, s0, v152
	s_mov_b32 s0, 0x3f22f983
	s_mov_b32 s6, 0xfe5163ab
	v_cndmask_b32_e32 v0, v0, v1, vcc
	v_lshl_add_u32 v14, v48, 3, v0
	v_mov_b32_e32 v0, 0x38800000
	v_bfrev_b32_e32 v1, 60
	v_cndmask_b32_e32 v0, v0, v1, vcc
	v_cvt_f32_ubyte0_e32 v1, v48
	v_mul_f32_e32 v1, 0xc0c90fdb, v1
	v_mul_f32_e32 v15, v0, v1
	v_mul_f32_e64 v0, |v15|, s0
	v_rndne_f32_e32 v0, v0
	s_mov_b32 s0, 0xbfc90fda
	v_fma_f32 v1, v0, s0, |v15|
	v_and_b32_e32 v16, 0x7fffffff, v15
	v_fmamk_f32 v1, v0, 0xb3a22168, v1
	v_cvt_i32_f32_e32 v17, v0
	v_fmamk_f32 v18, v0, 0xa7c234c4, v1
	v_lshrrev_b32_e32 v0, 23, v16
	v_add_u32_e32 v0, 0xffffff88, v0
	v_not_b32_e32 v1, 63
	v_cmp_lt_u32_e32 vcc, 63, v0
	v_mov_b32_e32 v3, 0
	s_movk_i32 s10, 0x1f8
	v_cndmask_b32_e32 v1, 0, v1, vcc
	v_add_u32_e32 v0, v1, v0
	v_not_b32_e32 v1, 31
	v_cmp_lt_u32_e64 s[0:1], 31, v0
	s_nop 1
	v_cndmask_b32_e64 v2, 0, v1, s[0:1]
	v_add_u32_e32 v0, v2, v0
	v_cmp_lt_u32_e64 s[4:5], 31, v0
	s_nop 1
	v_cndmask_b32_e64 v1, 0, v1, s[4:5]
	v_add_u32_e32 v19, v1, v0
	v_and_b32_e32 v0, 0x7fffff, v16
	v_or_b32_e32 v20, 0x800000, v0
	v_mad_u64_u32 v[0:1], s[6:7], v20, s6, 0
	v_mov_b32_e32 v2, v1
	s_mov_b32 s6, 0x3c439041
	v_mad_u64_u32 v[4:5], s[6:7], v20, s6, v[2:3]
	v_mov_b32_e32 v2, v5
	s_mov_b32 s6, 0xdb629599
	v_mad_u64_u32 v[6:7], s[6:7], v20, s6, v[2:3]
	v_mov_b32_e32 v2, v7
	s_mov_b32 s6, 0xf534ddc0
	v_mad_u64_u32 v[8:9], s[6:7], v20, s6, v[2:3]
	v_mov_b32_e32 v2, v9
	s_mov_b32 s6, 0xfc2757d1
	v_mad_u64_u32 v[10:11], s[6:7], v20, s6, v[2:3]
	v_mov_b32_e32 v2, v11
	s_mov_b32 s6, 0x4e441529
	v_mad_u64_u32 v[12:13], s[6:7], v20, s6, v[2:3]
	v_mov_b32_e32 v2, v13
	s_mov_b32 s6, 0xa2f9836e
	v_mad_u64_u32 v[2:3], s[6:7], v20, s6, v[2:3]
	v_cndmask_b32_e32 v1, v12, v8, vcc
	v_cndmask_b32_e32 v2, v2, v10, vcc
	v_cndmask_b32_e32 v3, v3, v12, vcc
	v_cndmask_b32_e64 v5, v2, v1, s[0:1]
	v_cndmask_b32_e64 v2, v3, v2, s[0:1]
	v_cndmask_b32_e32 v3, v10, v6, vcc
	v_cndmask_b32_e64 v1, v1, v3, s[0:1]
	v_cndmask_b32_e32 v4, v8, v4, vcc
	v_cndmask_b32_e64 v2, v2, v5, s[4:5]
	v_cndmask_b32_e64 v5, v5, v1, s[4:5]
	v_sub_u32_e32 v7, 32, v19
	v_cndmask_b32_e64 v3, v3, v4, s[0:1]
	v_alignbit_b32 v9, v2, v5, v7
	v_cmp_eq_u32_e64 s[6:7], 0, v19
	v_cndmask_b32_e64 v1, v1, v3, s[4:5]
	v_alignbit_b32 v8, v5, v1, v7
	v_cndmask_b32_e64 v2, v9, v2, s[6:7]
	v_cndmask_b32_e32 v0, v6, v0, vcc
	v_bfe_u32 v10, v2, 29, 1
	v_cndmask_b32_e64 v5, v8, v5, s[6:7]
	v_cndmask_b32_e64 v0, v4, v0, s[0:1]
	v_lshrrev_b32_e32 v9, 29, v2
	v_lshrrev_b32_e32 v11, 30, v2
	v_alignbit_b32 v2, v2, v5, 30
	v_sub_u32_e32 v8, 0, v10
	v_cndmask_b32_e64 v0, v3, v0, s[4:5]
	v_xor_b32_e32 v2, v2, v8
	v_alignbit_b32 v3, v1, v0, v7
	v_cndmask_b32_e64 v1, v3, v1, s[6:7]
	v_ffbh_u32_e32 v4, v2
	v_alignbit_b32 v3, v5, v1, 30
	v_min_u32_e32 v4, 32, v4
	v_alignbit_b32 v0, v1, v0, 30
	v_xor_b32_e32 v3, v3, v8
	v_sub_u32_e32 v5, 31, v4
	v_xor_b32_e32 v0, v0, v8
	v_alignbit_b32 v2, v2, v3, v5
	v_alignbit_b32 v0, v3, v0, v5
	v_lshlrev_b32_e32 v7, 31, v9
	v_alignbit_b32 v1, v2, v0, 9
	v_add_u32_e32 v11, v10, v11
	v_lshrrev_b32_e32 v6, 9, v2
	v_or_b32_e32 v9, 0.5, v7
	v_lshlrev_b32_e32 v10, 23, v4
	v_ffbh_u32_e32 v2, v1
	v_sub_u32_e32 v9, v9, v10
	v_min_u32_e32 v2, 32, v2
	v_or_b32_e32 v6, v6, v9
	v_add_lshl_u32 v3, v2, v4, 23
	v_not_b32_e32 v2, v2
	s_mov_b32 s0, 0x3fc90fda
	v_mul_f32_e32 v9, 0x3fc90fda, v6
	v_or_b32_e32 v7, 0x33000000, v7
	v_alignbit_b32 v0, v1, v0, v2
	v_sub_u32_e32 v3, v7, v3
	v_lshrrev_b32_e32 v0, 9, v0
	v_fma_f32 v1, v6, s0, -v9
	v_or_b32_e32 v0, v3, v0
	v_fmamk_f32 v1, v6, 0x33a22168, v1
	v_fmac_f32_e32 v1, 0x3fc90fda, v0
	s_brev_b32 s0, 18
	v_add_f32_e32 v0, v9, v1
	v_cmp_lt_f32_e64 vcc, |v15|, s0
	v_mov_b32_e32 v3, 0x3c0881c4
	s_brev_b32 s0, 1
	v_cndmask_b32_e32 v0, v0, v18, vcc
	v_mul_f32_e32 v2, v0, v0
	v_fmac_f32_e32 v3, 0xb94c1982, v2
	v_fmaak_f32 v3, v2, v3, 0xbe2aaa9d
	v_mul_f32_e32 v3, v2, v3
	v_fmac_f32_e32 v0, v0, v3
	v_mov_b32_e32 v3, 0xbab64f3b
	v_fmac_f32_e32 v3, 0x37d75334, v2
	v_fmaak_f32 v3, v2, v3, 0x3d2aabf7
	v_cndmask_b32_e32 v1, v11, v17, vcc
	v_fmaak_f32 v3, v2, v3, 0xbf000004
	v_fma_f32 v2, v2, v3, 1.0
	v_lshlrev_b32_e32 v3, 30, v1
	v_and_b32_e32 v1, 1, v1
	v_cmp_eq_u32_e32 vcc, 0, v1
	v_and_b32_e32 v4, 0x80000000, v3
	s_nop 0
	v_cndmask_b32_e32 v1, v2, v0, vcc
	v_xor_b32_e32 v1, v1, v15
	v_xor_b32_e32 v0, 0x80000000, v0
	v_xor_b32_e32 v1, v1, v16
	v_cndmask_b32_e32 v0, v0, v2, vcc
	v_xor_b32_e32 v1, v1, v4
	v_bitop3_b32 v0, v0, v3, s0 bitop3:0x78
	v_mov_b32_e32 v2, 0x7fc00000
	v_cmp_class_f32_e64 vcc, v15, s10
	s_nop 1
	v_cndmask_b32_e32 v0, v2, v0, vcc
	v_cndmask_b32_e32 v1, v2, v1, vcc
	ds_write_b64 v14, v[0:1]

; __device__ __forceinline__ void hyena_phase(LAS unsigned char* L, const Args& a, int vcu, int G) {
;     ...
;     if (vcu < 4096) HY_PREFETCH(vcu);
;     for (int unit = vcu; unit < 4096; unit += G) {
.LBB0_1057:
	s_or_b64 exec, exec, s[42:43]
	s_add_i32 s96, s96, 8
	s_cmp_ge_i32 s96, s75
	s_cselect_b64 s[42:43], -1, 0
	s_and_b64 vcc, exec, s[42:43]
	s_cbranch_vccnz .LBB0_1083
	s_ashr_i32 s21, s96, 2
	s_and_b32 s52, s21, -2
	s_ashr_i32 s53, s52, 31
	s_lshl_b64 s[44:45], s[52:53], 17
	s_add_u32 s23, s58, s44
	s_addc_u32 s33, s59, s45
	s_lshl_b32 s21, s96, 13
	s_and_b32 s21, s21, 0xe000
	s_lshl_b32 s21, s21, 1
	s_add_u32 s23, s23, s21
	s_addc_u32 s33, s33, 0
	s_add_u32 s44, s23, 0x8000000
	s_addc_u32 s45, s33, 0
	global_load_dwordx4 v[0:3], v116, s[44:45]
	v_lshl_add_u64 v[4:5], s[44:45], 0, v[116:117]
	v_mov_b32_e32 v162, 0
	v_mov_b32_e32 v161, 0
	s_and_saveexec_b64 s[48:49], s[10:11]
	s_cbranch_execz .LBB0_1060
	global_load_dword v161, v[4:5], off offset:-4

; #define LAS __attribute__((address_space(3)))
; template <bool INV, int LST, bool HALF = false> __device__ __forceinline__ void fft_pass16(LAS cf* z, const LAS cf* Thi, const LAS cf* Tlo, int tid) {
;     constexpr int st = 1 << LST;
;     cf w[16];
; #pragma unroll 1
;     for (int it = 0; it < 2; ++it) {
;         const int g = tid + 512 * it; const int j0 = g & (st - 1); const int base = ((g >> LST) << (LST + 4)) + j0; const int phb = PH(base);
;         if (LST == 10 || it == 0) {
;             const int e1 = j0 << (10 - LST);
;             w[1] = cmul(Thi[e1 >> 7], Tlo[e1 & 127]);
;             w[2] = cmul(w[1], w[1]); w[3] = cmul(w[2], w[1]); w[4] = cmul(w[2], w[2]); w[5] = cmul(w[4], w[1]); w[6] = cmul(w[3], w[3]); w[7] = cmul(w[4], w[3]); w[8] = cmul(w[4], w[4]);
; #pragma unroll
;             for (int q = 9; q < 16; ++q) w[q] = cmul(w[8], w[q - 8]);
;         }
;         cf x[16];
;         if (!INV) {
; #pragma unroll
;             for (int m = 0; m < 16; ++m) { if (HALF && m >= 8) x[m] = (cf){0.f, 0.f}; else x[m] = z[pass_pos<LST>(base, phb, m)]; }
;             dft16<false, HALF>(x);
; #pragma unroll
;             for (int q = 0; q < 16; ++q) { cf y = x[4 * (q & 3) + (q >> 2)]; if (q) y = cmul(y, w[q]); z[pass_pos<LST>(base, phb, q)] = y; }
.LBB0_1084:
	v_add_u32_e32 v21, s52, v152
	v_and_b32_e32 v22, 0x3ff, v21
	v_lshlrev_b32_e32 v23, 4, v21
	v_lshrrev_b32_e32 v21, 4, v21
	v_and_b32_e32 v23, 0x4000, v23
	v_and_b32_e32 v29, 60, v21
	v_and_b32_e32 v21, 56, v21
	v_bitop3_b32 v22, v23, v29, v22 bitop3:0x36
	v_add_u32_e32 v21, 0, v21
	v_lshl_add_u32 v29, v22, 3, 0
	v_add_u32_e32 v21, 0x20000, v21
	ds_read2st64_b64 v[84:87], v29 offset1:16
	ds_read2st64_b64 v[88:91], v29 offset0:32 offset1:48
	ds_read2st64_b64 v[92:95], v29 offset0:64 offset1:80
	ds_read2st64_b64 v[96:99], v29 offset0:96 offset1:112
	v_add_u32_e32 v30, 0x10000, v29
	v_add_u32_e32 v110, 0x1e000, v29
	v_add_u32_e32 v37, 0x12000, v29
	v_add_u32_e32 v41, 0x14000, v29
	v_add_u32_e32 v76, 0x16000, v29
	v_add_u32_e32 v78, 0x18000, v29
	v_add_u32_e32 v80, 0x1a000, v29
	v_add_u32_e32 v82, 0x1c000, v29
	ds_read_b64 v[22:23], v21
	ds_read_b64 v[30:31], v30
	ds_read_b64 v[38:39], v37
	ds_read_b64 v[42:43], v120
	ds_read_b64 v[100:101], v41
	ds_read_b64 v[102:103], v76
	ds_read_b64 v[104:105], v78
	ds_read_b64 v[106:107], v80
	ds_read_b64 v[108:109], v82
	ds_read_b64 v[110:111], v110
	s_waitcnt lgkmcnt(6)
	v_pk_mul_f32 v[112:113], v[22:23], v[42:43] op_sel:[0,0] op_sel_hi:[0,1]
	s_mov_b32 s21, s22
	v_pk_fma_f32 v[22:23], v[22:23], v[42:43], v[112:113] op_sel:[1,1,0] op_sel_hi:[1,0,1] neg_lo:[1,0,0]
	s_mov_b32 s23, s20
	v_pk_mul_f32 v[42:43], v[22:23], v[22:23] op_sel:[0,0] op_sel_hi:[0,1]
	v_pk_mul_f32 v[112:113], v[86:87], v[22:23] op_sel:[0,0] op_sel_hi:[0,1] neg_hi:[0,1]
	s_mov_b32 s48, s25
	v_pk_fma_f32 v[42:43], v[22:23], v[22:23], v[42:43] op_sel:[1,1,0] op_sel_hi:[1,0,1] neg_lo:[1,0,0]
	v_pk_fma_f32 v[86:87], v[86:87], v[22:23], v[112:113] op_sel:[1,1,0] op_sel_hi:[1,0,1]
	s_mov_b32 s49, s24
	v_pk_mul_f32 v[112:113], v[42:43], v[22:23] op_sel:[0,0] op_sel_hi:[0,1]
	v_pk_mul_f32 v[114:115], v[42:43], v[42:43] op_sel:[0,0] op_sel_hi:[0,1]
	v_pk_mul_f32 v[230:231], v[88:89], v[42:43] op_sel:[0,0] op_sel_hi:[0,1] neg_hi:[0,1]
	s_movk_i32 s52, 0x200
	v_pk_fma_f32 v[112:113], v[42:43], v[22:23], v[112:113] op_sel:[1,1,0] op_sel_hi:[1,0,1] neg_lo:[1,0,0]
	v_pk_fma_f32 v[114:115], v[42:43], v[42:43], v[114:115] op_sel:[1,1,0] op_sel_hi:[1,0,1] neg_lo:[1,0,0]
	v_pk_fma_f32 v[88:89], v[88:89], v[42:43], v[230:231] op_sel:[1,1,0] op_sel_hi:[1,0,1]
	s_and_b64 vcc, exec, s[46:47]
	v_pk_mul_f32 v[230:231], v[114:115], v[22:23] op_sel:[0,0] op_sel_hi:[0,1]
	v_pk_mul_f32 v[232:233], v[112:113], v[112:113] op_sel:[0,0] op_sel_hi:[0,1]
	v_pk_mul_f32 v[234:235], v[114:115], v[112:113] op_sel:[0,0] op_sel_hi:[0,1]
	v_pk_mul_f32 v[236:237], v[114:115], v[114:115] op_sel:[0,0] op_sel_hi:[0,1]
	v_pk_mul_f32 v[238:239], v[90:91], v[112:113] op_sel:[0,0] op_sel_hi:[0,1] neg_hi:[0,1]
	v_pk_mul_f32 v[240:241], v[92:93], v[114:115] op_sel:[0,0] op_sel_hi:[0,1] neg_hi:[0,1]
	s_nop 0
	v_pk_fma_f32 v[230:231], v[114:115], v[22:23], v[230:231] op_sel:[1,1,0] op_sel_hi:[1,0,1] neg_lo:[1,0,0]
	v_pk_fma_f32 v[232:233], v[112:113], v[112:113], v[232:233] op_sel:[1,1,0] op_sel_hi:[1,0,1] neg_lo:[1,0,0]
	v_pk_fma_f32 v[234:235], v[114:115], v[112:113], v[234:235] op_sel:[1,1,0] op_sel_hi:[1,0,1] neg_lo:[1,0,0]
	v_pk_fma_f32 v[236:237], v[114:115], v[114:115], v[236:237] op_sel:[1,1,0] op_sel_hi:[1,0,1] neg_lo:[1,0,0]
	v_pk_fma_f32 v[90:91], v[90:91], v[112:113], v[238:239] op_sel:[1,1,0] op_sel_hi:[1,0,1]
	v_pk_fma_f32 v[92:93], v[92:93], v[114:115], v[240:241] op_sel:[1,1,0] op_sel_hi:[1,0,1]
	s_nop 0
	v_pk_mul_f32 v[252:253], v[94:95], v[230:231] op_sel:[0,0] op_sel_hi:[0,1] neg_hi:[0,1]
	v_pk_mul_f32 v[216:217], v[96:97], v[232:233] op_sel:[0,0] op_sel_hi:[0,1] neg_hi:[0,1]
	v_pk_mul_f32 v[226:227], v[98:99], v[234:235] op_sel:[0,0] op_sel_hi:[0,1] neg_hi:[0,1]
	v_pk_mul_f32 v[238:239], v[236:237], v[22:23] op_sel:[0,0] op_sel_hi:[0,1]
	v_pk_mul_f32 v[240:241], v[236:237], v[42:43] op_sel:[0,0] op_sel_hi:[0,1]
	v_pk_mul_f32 v[242:243], v[236:237], v[112:113] op_sel:[0,0] op_sel_hi:[0,1]
	v_pk_mul_f32 v[244:245], v[236:237], v[114:115] op_sel:[0,0] op_sel_hi:[0,1]
	v_pk_mul_f32 v[182:183], v[30:31], v[236:237] op_sel:[0,0] op_sel_hi:[0,1] neg_hi:[0,1]
	v_pk_mul_f32 v[246:247], v[236:237], v[230:231] op_sel:[0,0] op_sel_hi:[0,1]
	s_nop 0
	v_pk_fma_f32 v[22:23], v[236:237], v[22:23], v[238:239] op_sel:[1,1,0] op_sel_hi:[1,0,1] neg_lo:[1,0,0]
	v_pk_fma_f32 v[42:43], v[236:237], v[42:43], v[240:241] op_sel:[1,1,0] op_sel_hi:[1,0,1] neg_lo:[1,0,0]
	v_pk_mul_f32 v[248:249], v[236:237], v[232:233] op_sel:[0,0] op_sel_hi:[0,1]
	v_pk_mul_f32 v[250:251], v[236:237], v[234:235] op_sel:[0,0] op_sel_hi:[0,1]
	v_pk_fma_f32 v[30:31], v[30:31], v[236:237], v[182:183] op_sel:[1,1,0] op_sel_hi:[1,0,1]
	v_pk_fma_f32 v[112:113], v[236:237], v[112:113], v[242:243] op_sel:[1,1,0] op_sel_hi:[1,0,1] neg_lo:[1,0,0]
	v_pk_fma_f32 v[114:115], v[236:237], v[114:115], v[244:245] op_sel:[1,1,0] op_sel_hi:[1,0,1] neg_lo:[1,0,0]
	v_pk_fma_f32 v[238:239], v[236:237], v[230:231], v[246:247] op_sel:[1,1,0] op_sel_hi:[1,0,1] neg_lo:[1,0,0]
	s_nop 0
	v_pk_fma_f32 v[240:241], v[236:237], v[232:233], v[248:249] op_sel:[1,1,0] op_sel_hi:[1,0,1] neg_lo:[1,0,0]
	v_pk_fma_f32 v[242:243], v[236:237], v[234:235], v[250:251] op_sel:[1,1,0] op_sel_hi:[1,0,1] neg_lo:[1,0,0]
	v_pk_fma_f32 v[94:95], v[94:95], v[230:231], v[252:253] op_sel:[1,1,0] op_sel_hi:[1,0,1]
	v_pk_fma_f32 v[96:97], v[96:97], v[232:233], v[216:217] op_sel:[1,1,0] op_sel_hi:[1,0,1]
	v_pk_fma_f32 v[98:99], v[98:99], v[234:235], v[226:227] op_sel:[1,1,0] op_sel_hi:[1,0,1]
	v_pk_mul_f32 v[182:183], v[38:39], v[22:23] op_sel:[0,0] op_sel_hi:[0,1] neg_hi:[0,1]
	s_waitcnt lgkmcnt(5)
; __device__ __forceinline__ cf add_mib(cf a, cf b) { cf r; asm("v_pk_add_f32 %0, %1, %2 op_sel:[0,1] op_sel_hi:[1,0] neg_hi:[0,1]" : "=v"(r) : "v"(a), "v"(b)); return r; }
; __device__ __forceinline__ cf add_pib(cf a, cf b) { cf r; asm("v_pk_add_f32 %0, %1, %2 op_sel:[0,1] op_sel_hi:[1,0] neg_lo:[0,1]" : "=v"(r) : "v"(a), "v"(b)); return r; }
; template <bool INV> __device__ __forceinline__ void dft4(cf& a0, cf& a1, cf& a2, cf& a3) {
;     const cf s0 = a0 + a2, s1 = a0 - a2, s2 = a1 + a3, s3 = a1 - a3;
;     a0 = s0 + s2; a2 = s0 - s2;
;     if (!INV) { a1 = add_mib(s1, s3); a3 = add_pib(s1, s3); }
;     else      { a1 = add_pib(s1, s3); a3 = add_mib(s1, s3); }
; }
; template <bool INV> __device__ __forceinline__ cf tw16(cf v, float c, float s) {
;     const float ss = INV ? s : -s; return (cf){v.x * c - v.y * ss, v.x * ss + v.y * c};
; }
; template <bool INV, bool HALFIN = false> __device__ __forceinline__ void dft16(cf (&x)[16]) {
; #pragma unroll
;     for (int m2 = 0; m2 < 4; ++m2) {
;         if (HALFIN) { const cf a0 = x[m2], a1 = x[4 + m2]; x[m2] = a0 + a1; x[8 + m2] = a0 - a1; x[4 + m2] = add_mib(a0, a1); x[12 + m2] = add_pib(a0, a1); }
;         else dft4<INV>(x[m2], x[4 + m2], x[8 + m2], x[12 + m2]);
;     }
;     constexpr float C1 = 0.9238795325112867f, S1 = 0.3826834323650898f, C2 = 0.7071067811865476f;
;     x[4 * 1 + 1] = tw16<INV>(x[5], C1, S1);  x[4 * 1 + 2] = tw16<INV>(x[6], C2, C2);   x[4 * 1 + 3] = tw16<INV>(x[7], S1, C1);
;     x[4 * 2 + 1] = tw16<INV>(x[9], C2, C2);  x[4 * 2 + 2] = tw16<INV>(x[10], 0.f, 1.f); x[4 * 2 + 3] = tw16<INV>(x[11], -C2, C2);
;     x[4 * 3 + 1] = tw16<INV>(x[13], S1, C1); x[4 * 3 + 2] = tw16<INV>(x[14], -C2, C2); x[4 * 3 + 3] = tw16<INV>(x[15], -C1, -S1);
; #pragma unroll
;     for (int q1 = 0; q1 < 4; ++q1) dft4<INV>(x[4 * q1], x[4 * q1 + 1], x[4 * q1 + 2], x[4 * q1 + 3]);
; }
	v_pk_mul_f32 v[216:217], v[100:101], v[42:43] op_sel:[0,0] op_sel_hi:[0,1] neg_hi:[0,1]
	s_waitcnt lgkmcnt(4)
	v_pk_mul_f32 v[226:227], v[102:103], v[112:113] op_sel:[0,0] op_sel_hi:[0,1] neg_hi:[0,1]
	s_waitcnt lgkmcnt(3)
	v_pk_mul_f32 v[230:231], v[104:105], v[114:115] op_sel:[0,0] op_sel_hi:[0,1] neg_hi:[0,1]
	s_waitcnt lgkmcnt(2)
	v_pk_mul_f32 v[232:233], v[106:107], v[238:239] op_sel:[0,0] op_sel_hi:[0,1] neg_hi:[0,1]
	s_waitcnt lgkmcnt(1)
	v_pk_mul_f32 v[234:235], v[108:109], v[240:241] op_sel:[0,0] op_sel_hi:[0,1] neg_hi:[0,1]
	v_pk_add_f32 v[244:245], v[84:85], v[30:31]
	v_pk_add_f32 v[30:31], v[84:85], v[30:31] neg_lo:[0,1] neg_hi:[0,1]
	v_pk_fma_f32 v[22:23], v[38:39], v[22:23], v[182:183] op_sel:[1,1,0] op_sel_hi:[1,0,1]
	v_pk_fma_f32 v[38:39], v[100:101], v[42:43], v[216:217] op_sel:[1,1,0] op_sel_hi:[1,0,1]
	v_pk_fma_f32 v[42:43], v[102:103], v[112:113], v[226:227] op_sel:[1,1,0] op_sel_hi:[1,0,1]
	v_pk_fma_f32 v[84:85], v[104:105], v[114:115], v[230:231] op_sel:[1,1,0] op_sel_hi:[1,0,1]
	v_pk_fma_f32 v[100:101], v[106:107], v[238:239], v[232:233] op_sel:[1,1,0] op_sel_hi:[1,0,1]
	v_pk_fma_f32 v[102:103], v[108:109], v[240:241], v[234:235] op_sel:[1,1,0] op_sel_hi:[1,0,1]
	s_waitcnt lgkmcnt(0)
	v_pk_mul_f32 v[236:237], v[110:111], v[242:243] op_sel:[0,0] op_sel_hi:[0,1] neg_hi:[0,1]
	s_mov_b64 s[46:47], 0
	v_pk_fma_f32 v[104:105], v[110:111], v[242:243], v[236:237] op_sel:[1,1,0] op_sel_hi:[1,0,1]
	v_pk_add_f32 v[106:107], v[92:93], v[84:85]
	v_pk_add_f32 v[84:85], v[92:93], v[84:85] neg_lo:[0,1] neg_hi:[0,1]
	v_pk_add_f32 v[92:93], v[86:87], v[22:23]
	v_pk_add_f32 v[22:23], v[86:87], v[22:23] neg_lo:[0,1] neg_hi:[0,1]
	v_pk_add_f32 v[86:87], v[94:95], v[100:101]
	v_pk_add_f32 v[94:95], v[94:95], v[100:101] neg_lo:[0,1] neg_hi:[0,1]
	v_pk_add_f32 v[100:101], v[88:89], v[38:39]
	v_pk_add_f32 v[38:39], v[88:89], v[38:39] neg_lo:[0,1] neg_hi:[0,1]
	v_pk_add_f32 v[88:89], v[96:97], v[102:103]
	v_pk_add_f32 v[96:97], v[96:97], v[102:103] neg_lo:[0,1] neg_hi:[0,1]
	v_pk_add_f32 v[102:103], v[90:91], v[42:43]
	v_pk_add_f32 v[42:43], v[90:91], v[42:43] neg_lo:[0,1] neg_hi:[0,1]
	v_pk_add_f32 v[90:91], v[98:99], v[104:105]
	v_pk_add_f32 v[98:99], v[98:99], v[104:105] neg_lo:[0,1] neg_hi:[0,1]
	v_pk_add_f32 v[104:105], v[244:245], v[106:107]
	v_pk_add_f32 v[108:109], v[30:31], v[84:85] op_sel:[0,1] op_sel_hi:[1,0] neg_lo:[0,1]
	v_pk_add_f32 v[30:31], v[30:31], v[84:85] op_sel:[0,1] op_sel_hi:[1,0] neg_hi:[0,1]
	v_pk_add_f32 v[84:85], v[92:93], v[86:87]
	v_pk_add_f32 v[86:87], v[92:93], v[86:87] neg_lo:[0,1] neg_hi:[0,1]
	v_pk_add_f32 v[92:93], v[22:23], v[94:95] op_sel:[0,1] op_sel_hi:[1,0] neg_lo:[0,1]
	v_pk_add_f32 v[22:23], v[22:23], v[94:95] op_sel:[0,1] op_sel_hi:[1,0] neg_hi:[0,1]
	v_pk_add_f32 v[94:95], v[100:101], v[88:89]
	v_pk_add_f32 v[88:89], v[100:101], v[88:89] neg_lo:[0,1] neg_hi:[0,1]
	v_pk_add_f32 v[100:101], v[38:39], v[96:97] op_sel:[0,1] op_sel_hi:[1,0] neg_lo:[0,1]
	v_pk_add_f32 v[38:39], v[38:39], v[96:97] op_sel:[0,1] op_sel_hi:[1,0] neg_hi:[0,1]
	v_pk_add_f32 v[96:97], v[102:103], v[90:91]
	v_pk_add_f32 v[90:91], v[102:103], v[90:91] neg_lo:[0,1] neg_hi:[0,1]
	v_pk_add_f32 v[102:103], v[42:43], v[98:99] op_sel:[0,1] op_sel_hi:[1,0] neg_lo:[0,1]
	v_pk_add_f32 v[42:43], v[42:43], v[98:99] op_sel:[0,1] op_sel_hi:[1,0] neg_hi:[0,1]
	v_mul_f32_e32 v76, 0x3ec3ef15, v93
	v_mul_f32_e32 v78, 0x3ec3ef15, v92
	v_pk_mul_f32 v[98:99], v[100:101], s[24:25] op_sel_hi:[1,0]
	v_pk_mul_f32 v[110:111], v[102:103], s[20:21] op_sel_hi:[1,0]
	v_pk_mul_f32 v[112:113], v[86:87], s[24:25] op_sel_hi:[1,0]
	v_pk_fma_f32 v[114:115], v[88:89], 0, v[88:89] op_sel:[0,0,1] op_sel_hi:[1,0,0] neg_lo:[0,0,1] neg_hi:[0,0,1]
	v_pk_fma_f32 v[88:89], v[88:89], 0, v[88:89] op_sel:[0,0,1] op_sel_hi:[1,0,0]
	v_mul_f32_e32 v80, 0x3f3504f3, v91
	v_pk_mul_f32 v[182:183], v[22:23], s[20:21] op_sel_hi:[1,0]
	v_mul_f32_e32 v82, 0x3f3504f3, v39
	v_pk_add_f32 v[226:227], v[104:105], v[94:95]
	v_pk_add_f32 v[94:95], v[104:105], v[94:95] neg_lo:[0,1] neg_hi:[0,1]
	v_pk_add_f32 v[104:105], v[84:85], v[96:97]
	v_pk_add_f32 v[84:85], v[84:85], v[96:97] neg_lo:[0,1] neg_hi:[0,1]
	v_pk_fma_f32 v[96:97], v[92:93], s[20:21], v[76:77] op_sel_hi:[1,1,0] neg_lo:[0,0,1] neg_hi:[0,0,1]
	v_pk_fma_f32 v[92:93], v[92:93], s[22:23], v[78:79] op_sel_hi:[1,1,0]
	v_pk_fma_f32 v[230:231], v[100:101], s[24:25], v[98:99] op_sel:[0,0,1] op_sel_hi:[1,0,0] neg_lo:[0,0,1] neg_hi:[0,0,1]
	v_pk_fma_f32 v[98:99], v[100:101], s[24:25], v[98:99] op_sel_hi:[1,0,0]
	v_pk_fma_f32 v[100:101], v[102:103], s[22:23], v[110:111] op_sel:[0,0,1] op_sel_hi:[1,0,0] neg_lo:[0,0,1] neg_hi:[0,0,1]
	v_pk_fma_f32 v[102:103], v[102:103], s[22:23], v[110:111] op_sel:[0,0,1] op_sel_hi:[1,0,0]
	v_pk_mul_f32 v[216:217], v[42:43], s[20:21] op_sel_hi:[0,1]
	v_pk_fma_f32 v[110:111], v[86:87], s[24:25], v[112:113] op_sel:[0,0,1] op_sel_hi:[1,0,0] neg_lo:[0,0,1] neg_hi:[0,0,1]
	v_pk_fma_f32 v[86:87], v[86:87], s[24:25], v[112:113] op_sel_hi:[1,0,0]
	v_mov_b32_e32 v115, v89
	v_pk_fma_f32 v[88:89], v[90:91], s[48:49], v[80:81] op_sel_hi:[0,1,0] neg_lo:[0,0,1] neg_hi:[0,0,1]
	v_pk_fma_f32 v[90:91], v[22:23], s[22:23], v[182:183] op_sel:[0,0,1] op_sel_hi:[1,0,0] neg_lo:[0,0,1] neg_hi:[0,0,1]
	v_pk_fma_f32 v[22:23], v[22:23], s[22:23], v[182:183] op_sel:[0,0,1] op_sel_hi:[1,0,0]
	v_pk_fma_f32 v[38:39], v[38:39], s[48:49], v[82:83] op_sel_hi:[0,1,0] neg_lo:[0,0,1] neg_hi:[0,0,1]
	s_mov_b32 s23, s37
	v_mov_b32_e32 v101, v103
	v_mov_b32_e32 v231, v99
	v_mov_b32_e32 v97, v93
	v_pk_add_f32 v[106:107], v[244:245], v[106:107] neg_lo:[0,1] neg_hi:[0,1]
	v_mov_b32_e32 v111, v87
	v_mov_b32_e32 v91, v23
; __device__ __forceinline__ float bf_lo(unsigned w) { return __uint_as_float(w << 16); }
; __device__ __forceinline__ float bf_hi(unsigned w) { return __uint_as_float(w & 0xffff0000u); }
; template <bool INV, int LST, bool HALF = false> __device__ __forceinline__ void fft_pass16(LAS cf* z, const LAS cf* Thi, const LAS cf* Tlo, int tid) {
;     ...
;             for (int m = 0; m < 16; ++m) { if (HALF && m >= 8) x[m] = (cf){0.f, 0.f}; else x[m] = z[pass_pos<LST>(base, phb, m)]; }
;             dft16<false, HALF>(x);
; #pragma unroll
;             for (int q = 0; q < 16; ++q) { cf y = x[4 * (q & 3) + (q >> 2)]; if (q) y = cmul(y, w[q]); z[pass_pos<LST>(base, phb, q)] = y; }
;         } else {
; #pragma unroll
;             for (int q = 0; q < 16; ++q) { cf y = z[pass_pos<LST>(base, phb, q)]; if (q) y = cmulc(y, w[q]); x[q] = y; }
;             dft16<true>(x);
; #pragma unroll
;             for (int m = 0; m < (HALF ? 8 : 16); ++m) z[pass_pos<LST>(base, phb, m)] = x[4 * (m & 3) + (m >> 2)];
;         }
;     }
;     __syncthreads();
; __device__ __forceinline__ void conv8(const unsigned* zp, int cidx, float w0, float w1, float w2, float cb, float (&o)[8]) {
;     const u32x4 cur = *(const u32x4*)(zp + 4 * cidx); const unsigned prev = cidx > 0 ? zp[4 * cidx - 1] : 0u; const unsigned next = cidx < SEQ / 8 - 1 ? zp[4 * cidx + 4] : 0u;
;     const float zz[10] = {bf_hi(prev), bf_lo(cur.x), bf_hi(cur.x), bf_lo(cur.y), bf_hi(cur.y), bf_lo(cur.z), bf_hi(cur.z), bf_lo(cur.w), bf_hi(cur.w), bf_lo(next)};
; #pragma unroll
;     for (int e = 0; e < 8; ++e) o[e] = w0 * zz[e] + w1 * zz[e + 1] + w2 * zz[e + 2] + cb;
; }
	v_pk_fma_f32 v[22:23], v[42:43], s[22:23], v[216:217] op_sel:[1,0,0] neg_lo:[0,0,1] neg_hi:[0,0,1]
	v_pk_add_f32 v[92:93], v[30:31], v[38:39]
	v_pk_add_f32 v[30:31], v[30:31], v[38:39] neg_lo:[0,1] neg_hi:[0,1]
	v_pk_add_f32 v[38:39], v[108:109], v[230:231]
	v_pk_add_f32 v[98:99], v[96:97], v[100:101]
	v_pk_add_f32 v[104:105], v[226:227], v[104:105]
	v_pk_add_f32 v[42:43], v[106:107], v[114:115]
	v_pk_add_f32 v[86:87], v[106:107], v[114:115] neg_lo:[0,1] neg_hi:[0,1]
	v_pk_add_f32 v[96:97], v[96:97], v[100:101] neg_lo:[0,1] neg_hi:[0,1]
	v_pk_add_f32 v[100:101], v[110:111], v[88:89]
	v_pk_add_f32 v[88:89], v[110:111], v[88:89] neg_lo:[0,1] neg_hi:[0,1]
	v_pk_add_f32 v[102:103], v[90:91], v[22:23]
	v_pk_add_f32 v[22:23], v[90:91], v[22:23] neg_lo:[0,1] neg_hi:[0,1]
	v_pk_add_f32 v[38:39], v[38:39], v[98:99]
	v_pk_add_f32 v[84:85], v[94:95], v[84:85] op_sel:[0,1] op_sel_hi:[1,0] neg_lo:[0,1]
	v_pk_add_f32 v[94:95], v[108:109], v[230:231] neg_lo:[0,1] neg_hi:[0,1]
	v_pk_add_f32 v[42:43], v[42:43], v[100:101]
	v_pk_add_f32 v[90:91], v[94:95], v[96:97] op_sel:[0,1] op_sel_hi:[1,0] neg_lo:[0,1]
	v_pk_add_f32 v[86:87], v[86:87], v[88:89] op_sel:[0,1] op_sel_hi:[1,0] neg_lo:[0,1]
	v_pk_add_f32 v[88:89], v[92:93], v[102:103]
	v_pk_add_f32 v[22:23], v[30:31], v[22:23] op_sel:[0,1] op_sel_hi:[1,0] neg_lo:[0,1]
	ds_write2st64_b64 v29, v[104:105], v[38:39] offset1:16
	ds_write2st64_b64 v29, v[42:43], v[88:89] offset0:32 offset1:48
	ds_write2st64_b64 v29, v[84:85], v[90:91] offset0:64 offset1:80
	ds_write2st64_b64 v29, v[86:87], v[22:23] offset0:96 offset1:112
	s_cbranch_vccnz .LBB0_1084
	s_waitcnt vmcnt(0)
	v_and_b32_e32 v23, 0xffff0000, v60
	v_and_b32_e32 v60, 0xffff0000, v61
	v_mov_b32_e32 v84, v69
	v_mov_b32_e32 v85, v65
	v_mov_b32_e32 v22, v60
	v_lshlrev_b32_e32 v30, 16, v61
	v_pk_mul_f32 v[22:23], v[84:85], v[22:23]
	v_lshlrev_b32_e32 v61, 16, v62
	v_pk_fma_f32 v[22:23], v[84:85], v[30:31], v[22:23] op_sel:[0,0,1] op_sel_hi:[1,0,0]
	v_and_b32_e32 v39, 16, v63
	v_and_b32_e32 v38, 0xffff0000, v62
	v_pk_fma_f32 v[22:23], v[66:67], v[60:61], v[22:23] op_sel:[1,0,0]
	v_lshlrev_b32_e32 v91, 16, v74
	v_pk_add_f32 v[42:43], v[70:71], v[22:23] op_sel:[1,0]
	v_pk_mov_b32 v[22:23], v[60:61], v[38:39] op_sel:[1,0]
	v_and_b32_e32 v87, 0xffff0000, v74
	v_pk_mul_f32 v[22:23], v[68:69], v[22:23] op_sel:[1,0]
	v_and_b32_e32 v88, 0xffff0000, v63
	v_mov_b32_e32 v86, v91
	v_lshlrev_b32_e32 v93, 16, v63
	v_mov_b32_e32 v92, v38
	v_pk_fma_f32 v[22:23], v[64:65], v[60:61], v[22:23] op_sel:[1,0,0]
	v_and_b32_e32 v89, 16, v74
	v_mov_b32_e32 v90, v88
	v_pk_fma_f32 v[22:23], v[66:67], v[92:93], v[22:23] op_sel:[1,0,0]
	v_pk_mul_f32 v[30:31], v[68:69], v[86:87] op_sel:[1,0]
	v_pk_add_f32 v[38:39], v[70:71], v[22:23] op_sel:[1,0]
	v_pk_mov_b32 v[22:23], v[92:93], v[88:89] op_sel:[1,0]
	v_pk_fma_f32 v[30:31], v[64:65], v[90:91], v[30:31] op_sel:[1,0,0]
	v_mov_b32_e32 v82, v87
	v_and_b32_e32 v96, 0xffff0000, v57
	v_pk_mul_f32 v[22:23], v[68:69], v[22:23] op_sel:[1,0]
	v_pk_fma_f32 v[30:31], v[66:67], v[82:83], v[30:31] op_sel:[1,0,0]
	v_and_b32_e32 v61, 0xffff0000, v56
	v_mov_b32_e32 v82, v68
	v_mov_b32_e32 v83, v64
	v_mov_b32_e32 v60, v96
	v_pk_fma_f32 v[22:23], v[64:65], v[92:93], v[22:23] op_sel:[1,0,0]
	v_lshlrev_b32_e32 v56, 16, v57
	v_and_b32_e32 v88, 0xffff0000, v59
	v_and_b32_e32 v93, 16, v59
	v_and_b32_e32 v92, 0xffff0000, v58
	v_lshlrev_b32_e32 v95, 16, v59
	v_lshlrev_b32_e32 v97, 16, v58
	v_pk_mul_f32 v[58:59], v[82:83], v[60:61]
	v_mov_b32_e32 v94, v92
	v_pk_fma_f32 v[56:57], v[82:83], v[56:57], v[58:59] op_sel:[0,0,1] op_sel_hi:[1,0,0]
	s_add_u32 s38, s14, s38
	v_pk_fma_f32 v[56:57], v[66:67], v[96:97], v[56:57] op_sel_hi:[0,1,1]
	v_pk_add_f32 v[62:63], v[70:71], v[56:57] op_sel_hi:[0,1]
	v_pk_mov_b32 v[56:57], v[96:97], v[92:93] op_sel:[1,0]
	v_and_b32_e32 v89, 16, v72
	v_pk_mul_f32 v[56:57], v[68:69], v[56:57] op_sel_hi:[0,1]
	v_pk_fma_f32 v[56:57], v[64:65], v[96:97], v[56:57] op_sel_hi:[0,1,1]
	v_pk_fma_f32 v[56:57], v[66:67], v[94:95], v[56:57] op_sel_hi:[0,1,1]
	s_addc_u32 s39, s15, s39
	v_pk_fma_f32 v[22:23], v[66:67], v[90:91], v[22:23] op_sel:[1,0,0]
	v_mov_b32_e32 v90, v88
	v_pk_add_f32 v[60:61], v[70:71], v[56:57] op_sel_hi:[0,1]
	v_pk_mov_b32 v[56:57], v[94:95], v[88:89] op_sel:[1,0]
	s_waitcnt lgkmcnt(0)
	s_barrier
; __device__ __forceinline__ unsigned pk2(float lo, float hi) { f32x2 v = {lo, hi}; bf16x2_t b = __builtin_convertvector(v, bf16x2_t); return __builtin_bit_cast(unsigned, b); }
; #define LAS __attribute__((address_space(3)))
; __device__ __forceinline__ float bf_lo(unsigned w) { return __uint_as_float(w << 16); }
; __device__ __forceinline__ void conv8(const unsigned* zp, int cidx, float w0, float w1, float w2, float cb, float (&o)[8]) {
;     const u32x4 cur = *(const u32x4*)(zp + 4 * cidx); const unsigned prev = cidx > 0 ? zp[4 * cidx - 1] : 0u; const unsigned next = cidx < SEQ / 8 - 1 ? zp[4 * cidx + 4] : 0u;
;     const float zz[10] = {bf_hi(prev), bf_lo(cur.x), bf_hi(cur.x), bf_lo(cur.y), bf_hi(cur.y), bf_lo(cur.z), bf_hi(cur.z), bf_lo(cur.w), bf_hi(cur.w), bf_lo(next)};
; #pragma unroll
;     for (int e = 0; e < 8; ++e) o[e] = w0 * zz[e] + w1 * zz[e + 1] + w2 * zz[e + 2] + cb;
; }
; __device__ __forceinline__ void hyena_phase(LAS unsigned char* L, const Args& a, int vcu, int G) {
;     ...
;         {
;             const float ska = skip[ca], skb = skip[ca + 1];
;             u32x4* ga = (u32x4*)(Gc + (size_t)ca * GLD + (size_t)b * SEQ); u32x4* gb = (u32x4*)(Gc + (size_t)(ca + 1) * GLD + (size_t)b * SEQ);
; #pragma unroll
;             for (int i = 0; i < 2; ++i) { const int cidx = tid + 512 * i;
;                 float ya[8], yb[8];
; #pragma unroll
;                 for (int e = 0; e < 8; e += 2) { const f32x4 y = *(LAS f32x4*)(z + PH(8 * cidx + e)); ya[e] = y[0]; yb[e] = y[1]; ya[e + 1] = y[2]; yb[e + 1] = y[3]; }
;                 u32x4 oa, ob;
;                 oa.x = pk2((ya[0] + ua[i][0] * ska) * xa[i][0], (ya[1] + ua[i][1] * ska) * xa[i][1]); oa.y = pk2((ya[2] + ua[i][2] * ska) * xa[i][2], (ya[3] + ua[i][3] * ska) * xa[i][3]);
;                 oa.z = pk2((ya[4] + ua[i][4] * ska) * xa[i][4], (ya[5] + ua[i][5] * ska) * xa[i][5]); oa.w = pk2((ya[6] + ua[i][6] * ska) * xa[i][6], (ya[7] + ua[i][7] * ska) * xa[i][7]);
;                 ob.x = pk2((yb[0] + ub[i][0] * skb) * xb[i][0], (yb[1] + ub[i][1] * skb) * xb[i][1]); ob.y = pk2((yb[2] + ub[i][2] * skb) * xb[i][2], (yb[3] + ub[i][3] * skb) * xb[i][3]);
;                 ob.z = pk2((yb[4] + ub[i][4] * skb) * xb[i][4], (yb[5] + ub[i][5] * skb) * xb[i][5]); ob.w = pk2((yb[6] + ub[i][6] * skb) * xb[i][6], (yb[7] + ub[i][7] * skb) * xb[i][7]);
;                 ga[cidx] = oa; gb[cidx] = ob; }
;         }
	global_load_dwordx2 v[88:89], v117, s[38:39]
	v_and_b32_e32 v87, 0xffff0000, v72
	v_lshlrev_b32_e32 v91, 16, v72
	v_lshlrev_b32_e32 v72, 16, v52
	v_and_b32_e32 v52, 0xffff0000, v52
	v_mov_b32_e32 v78, v52
	v_pk_mul_f32 v[78:79], v[84:85], v[78:79]
	v_and_b32_e32 v92, 0xffff0000, v53
	v_lshlrev_b32_e32 v53, 16, v53
	v_pk_fma_f32 v[78:79], v[84:85], v[72:73], v[78:79] op_sel:[0,0,1] op_sel_hi:[1,0,0]
	v_mov_b32_e32 v86, v91
	v_and_b32_e32 v93, 16, v54
	v_pk_fma_f32 v[78:79], v[66:67], v[52:53], v[78:79] op_sel:[1,0,0]
	v_pk_mul_f32 v[56:57], v[68:69], v[56:57] op_sel_hi:[0,1]
	v_pk_mul_f32 v[58:59], v[68:69], v[86:87] op_sel_hi:[0,1]
	v_pk_add_f32 v[84:85], v[70:71], v[78:79] op_sel:[1,0]
	v_pk_mov_b32 v[78:79], v[52:53], v[92:93] op_sel:[1,0]
	v_pk_fma_f32 v[56:57], v[64:65], v[94:95], v[56:57] op_sel_hi:[0,1,1]
	v_pk_fma_f32 v[58:59], v[64:65], v[90:91], v[58:59] op_sel_hi:[0,1,1]
	v_mov_b32_e32 v80, v87
	v_pk_mul_f32 v[78:79], v[68:69], v[78:79] op_sel:[1,0]
	v_pk_fma_f32 v[56:57], v[66:67], v[90:91], v[56:57] op_sel_hi:[0,1,1]
	v_pk_fma_f32 v[58:59], v[66:67], v[80:81], v[58:59] op_sel_hi:[0,1,1]
	v_and_b32_e32 v81, 0xffff0000, v55
	v_and_b32_e32 v87, 16, v55
	v_and_b32_e32 v86, 0xffff0000, v54
	v_lshlrev_b32_e32 v91, 16, v55
	v_lshlrev_b32_e32 v55, 16, v54
	v_mov_b32_e32 v54, v92
	v_pk_fma_f32 v[52:53], v[64:65], v[52:53], v[78:79] op_sel:[1,0,0]
	v_mov_b32_e32 v90, v86
	v_pk_fma_f32 v[52:53], v[66:67], v[54:55], v[52:53] op_sel:[1,0,0]
	v_mov_b32_e32 v80, v91
	v_pk_add_f32 v[92:93], v[70:71], v[52:53] op_sel:[1,0]
	v_pk_mov_b32 v[52:53], v[54:55], v[86:87] op_sel:[1,0]
	v_mov_b32_e32 v76, v81
	v_pk_mul_f32 v[52:53], v[68:69], v[52:53] op_sel:[1,0]
	v_lshlrev_b32_e32 v79, 16, v51
	v_pk_fma_f32 v[52:53], v[64:65], v[54:55], v[52:53] op_sel:[1,0,0]
	v_and_b32_e32 v55, 0xffff0000, v51
	v_pk_fma_f32 v[52:53], v[66:67], v[90:91], v[52:53] op_sel:[1,0,0]
	v_mov_b32_e32 v54, v79
	v_pk_add_f32 v[86:87], v[70:71], v[52:53] op_sel:[1,0]
	v_pk_mul_f32 v[52:53], v[68:69], v[80:81] op_sel:[1,0]
	v_and_b32_e32 v80, 0xffff0000, v49
	v_pk_fma_f32 v[52:53], v[64:65], v[90:91], v[52:53] op_sel:[1,0,0]
	v_lshlrev_b32_e32 v49, 16, v49
	v_pk_fma_f32 v[52:53], v[66:67], v[76:77], v[52:53] op_sel:[1,0,0]
	v_and_b32_e32 v81, 16, v50
	v_pk_add_f32 v[90:91], v[70:71], v[52:53] op_sel:[1,0]
	v_lshlrev_b32_e32 v52, 16, v48
	v_and_b32_e32 v48, 0xffff0000, v48
	v_mov_b32_e32 v74, v48
	v_pk_mul_f32 v[74:75], v[82:83], v[74:75]
	v_and_b32_e32 v77, 16, v51
	v_pk_fma_f32 v[52:53], v[82:83], v[52:53], v[74:75] op_sel:[0,0,1] op_sel_hi:[1,0,0]
	v_and_b32_e32 v76, 0xffff0000, v50
	v_pk_fma_f32 v[52:53], v[66:67], v[48:49], v[52:53] op_sel_hi:[0,1,1]
	v_pk_add_f32 v[82:83], v[70:71], v[52:53] op_sel_hi:[0,1]
	v_pk_mov_b32 v[52:53], v[48:49], v[80:81] op_sel:[1,0]
	v_lshlrev_b32_e32 v51, 16, v50
	v_pk_mul_f32 v[52:53], v[68:69], v[52:53] op_sel_hi:[0,1]
	v_mov_b32_e32 v50, v80
	v_pk_fma_f32 v[48:49], v[64:65], v[48:49], v[52:53] op_sel_hi:[0,1,1]
	v_pk_fma_f32 v[48:49], v[66:67], v[50:51], v[48:49] op_sel_hi:[0,1,1]
	v_pk_add_f32 v[80:81], v[70:71], v[48:49] op_sel_hi:[0,1]
	v_pk_mov_b32 v[48:49], v[50:51], v[76:77] op_sel:[1,0]
	v_mov_b32_e32 v78, v76
	v_pk_mul_f32 v[48:49], v[68:69], v[48:49] op_sel_hi:[0,1]
	v_pk_fma_f32 v[48:49], v[64:65], v[50:51], v[48:49] op_sel_hi:[0,1,1]
	v_pk_fma_f32 v[48:49], v[66:67], v[78:79], v[48:49] op_sel_hi:[0,1,1]
	v_pk_add_f32 v[94:95], v[70:71], v[48:49] op_sel_hi:[0,1]
	v_pk_mul_f32 v[48:49], v[68:69], v[54:55] op_sel_hi:[0,1]
	v_pk_fma_f32 v[48:49], v[64:65], v[78:79], v[48:49] op_sel_hi:[0,1,1]
	v_mov_b32_e32 v72, v55
	v_pk_fma_f32 v[48:49], v[66:67], v[72:73], v[48:49] op_sel_hi:[0,1,1]
	v_pk_add_f32 v[22:23], v[70:71], v[22:23] op_sel:[1,0]
	v_pk_add_f32 v[30:31], v[70:71], v[30:31] op_sel:[1,0]
	v_pk_add_f32 v[56:57], v[70:71], v[56:57] op_sel_hi:[0,1]
	v_pk_add_f32 v[58:59], v[70:71], v[58:59] op_sel_hi:[0,1]
	v_pk_add_f32 v[96:97], v[70:71], v[48:49] op_sel_hi:[0,1]
	ds_read_b128 v[48:51], v178
	ds_read_b128 v[52:55], v179
	ds_read_b128 v[64:67], v180
	ds_read_b128 v[68:71], v181
	ds_read_b128 v[72:75], v177
	s_lshl_b64 s[38:39], s[44:45], 1
	s_waitcnt lgkmcnt(4)
	v_mov_b32_e32 v76, v48
	v_mov_b32_e32 v77, v50
	s_waitcnt lgkmcnt(3)
	v_mov_b32_e32 v78, v52
	v_mov_b32_e32 v79, v54
	s_add_u32 s21, s60, s38
	s_waitcnt vmcnt(0)
	v_pk_fma_f32 v[76:77], v[132:133], v[88:89], v[76:77] op_sel_hi:[1,0,1]
	v_pk_fma_f32 v[78:79], v[128:129], v[88:89], v[78:79] op_sel_hi:[1,0,1]
	s_addc_u32 s23, s61, s39
	v_pk_mul_f32 v[76:77], v[82:83], v[76:77]
	v_pk_mul_f32 v[78:79], v[80:81], v[78:79]
	s_add_u32 s38, s21, s73
	v_cvt_pk_bf16_f32 v76, v76, v77
	v_cvt_pk_bf16_f32 v77, v78, v79
	s_waitcnt lgkmcnt(2)
	v_mov_b32_e32 v78, v64
	v_mov_b32_e32 v79, v66
	v_mov_b32_e32 v50, v49
	v_mov_b32_e32 v54, v53
	s_addc_u32 s39, s23, 0
	s_lshl_b64 s[40:41], s[40:41], 1
	v_pk_fma_f32 v[78:79], v[130:131], v[88:89], v[78:79] op_sel_hi:[1,0,1]
	v_pk_fma_f32 v[48:49], v[134:135], v[88:89], v[50:51] op_sel:[0,1,0]
	v_pk_fma_f32 v[50:51], v[136:137], v[88:89], v[54:55] op_sel:[0,1,0]
	s_add_u32 s21, s60, s40
	v_pk_mul_f32 v[78:79], v[94:95], v[78:79]
	s_waitcnt lgkmcnt(1)
	v_mov_b32_e32 v94, v68
	v_mov_b32_e32 v95, v70
	v_pk_mul_f32 v[48:49], v[84:85], v[48:49]
	v_pk_mul_f32 v[50:51], v[92:93], v[50:51]
	v_mov_b32_e32 v66, v65
	v_mov_b32_e32 v70, v69
	s_addc_u32 s23, s61, s41
	ds_read_b128 v[80:83], v210
	v_pk_fma_f32 v[94:95], v[126:127], v[88:89], v[94:95] op_sel_hi:[1,0,1]
	v_cvt_pk_bf16_f32 v48, v48, v49
	v_cvt_pk_bf16_f32 v49, v50, v51
	v_pk_fma_f32 v[50:51], v[140:141], v[88:89], v[66:67] op_sel:[0,1,0]
	v_pk_fma_f32 v[52:53], v[138:139], v[88:89], v[70:71] op_sel:[0,1,0]
	s_add_u32 s40, s21, s73
	v_pk_mul_f32 v[94:95], v[96:97], v[94:95]
	v_pk_mul_f32 v[50:51], v[86:87], v[50:51]
	v_pk_mul_f32 v[52:53], v[90:91], v[52:53]
	s_addc_u32 s41, s23, 0
	v_cvt_pk_bf16_f32 v78, v78, v79
	v_cvt_pk_bf16_f32 v79, v94, v95
	v_cvt_pk_bf16_f32 v50, v50, v51
	v_cvt_pk_bf16_f32 v51, v52, v53
	global_store_dwordx4 v124, v[76:79], s[38:39]
	global_store_dwordx4 v124, v[48:51], s[40:41]
	s_waitcnt lgkmcnt(1)
; #define LAS __attribute__((address_space(3)))
; __device__ __forceinline__ void hyena_phase(LAS unsigned char* L, const Args& a, int vcu, int G) {
;     ...
;             u32x4* ga = (u32x4*)(Gc + (size_t)ca * GLD + (size_t)b * SEQ); u32x4* gb = (u32x4*)(Gc + (size_t)(ca + 1) * GLD + (size_t)b * SEQ);
; #pragma unroll
;             for (int i = 0; i < 2; ++i) { const int cidx = tid + 512 * i;
;                 float ya[8], yb[8];
; #pragma unroll
;                 for (int e = 0; e < 8; e += 2) { const f32x4 y = *(LAS f32x4*)(z + PH(8 * cidx + e)); ya[e] = y[0]; yb[e] = y[1]; ya[e + 1] = y[2]; yb[e + 1] = y[3]; }
;                 u32x4 oa, ob;
;                 oa.x = pk2((ya[0] + ua[i][0] * ska) * xa[i][0], (ya[1] + ua[i][1] * ska) * xa[i][1]); oa.y = pk2((ya[2] + ua[i][2] * ska) * xa[i][2], (ya[3] + ua[i][3] * ska) * xa[i][3]);
;                 oa.z = pk2((ya[4] + ua[i][4] * ska) * xa[i][4], (ya[5] + ua[i][5] * ska) * xa[i][5]); oa.w = pk2((ya[6] + ua[i][6] * ska) * xa[i][6], (ya[7] + ua[i][7] * ska) * xa[i][7]);
;                 ob.x = pk2((yb[0] + ub[i][0] * skb) * xb[i][0], (yb[1] + ub[i][1] * skb) * xb[i][1]); ob.y = pk2((yb[2] + ub[i][2] * skb) * xb[i][2], (yb[3] + ub[i][3] * skb) * xb[i][3]);
;                 ob.z = pk2((yb[4] + ub[i][4] * skb) * xb[i][4], (yb[5] + ub[i][5] * skb) * xb[i][5]); ob.w = pk2((yb[6] + ub[i][6] * skb) * xb[i][6], (yb[7] + ub[i][7] * skb) * xb[i][7]);
;                 ga[cidx] = oa; gb[cidx] = ob; }
;         }
;         __syncthreads();
; __device__ __forceinline__ void transpose_phase(LAS unsigned char* L, const Args& a) {
;     ...
;     if (gw < 16 * 1024) TP_LOAD(gw);
;     for (int item = gw; item < 16 * 1024; item += NGW) {
;         const int cblk = item & 15, tblk = item >> 4; const int c0 = cblk * 64, t0 = tblk * 64;
; #pragma unroll
;         for (int j = 0; j < 8; ++j) { const int c = 8 * j + (lane >> 3), ch = lane & 7; const u32x4 v = nx[j];
;             LAS unsigned* d = (LAS unsigned*)(T + c * 132 + ch * 16); d[0] = v.x; d[1] = v.y; d[2] = v.z; d[3] = v.w; }
;         if (item + NGW < 16 * 1024) TP_LOAD(item + NGW);
;         asm volatile("s_waitcnt lgkmcnt(0)" ::: "memory");
; #pragma unroll
;         for (int j = 0; j < 8; ++j) { const int t = 8 * j + (lane >> 3), ch = lane & 7; const LAS unsigned short* s = (const LAS unsigned short*)(T + (8 * ch) * 132 + 2 * t);
	v_mov_b32_e32 v64, v72
	v_mov_b32_e32 v65, v74
	ds_read_b128 v[48:51], v211
	ds_read_b128 v[52:55], v212
	v_pk_fma_f32 v[64:65], v[142:143], v[88:89], v[64:65] op_sel_hi:[1,0,1]
	v_mov_b32_e32 v74, v73
	v_pk_mul_f32 v[62:63], v[62:63], v[64:65]
	s_waitcnt lgkmcnt(2)
	v_mov_b32_e32 v64, v80
	v_mov_b32_e32 v65, v82
	v_pk_fma_f32 v[64:65], v[144:145], v[88:89], v[64:65] op_sel_hi:[1,0,1]
	v_cvt_pk_bf16_f32 v62, v62, v63
	v_pk_mul_f32 v[60:61], v[60:61], v[64:65]
	v_mov_b32_e32 v82, v81
	v_cvt_pk_bf16_f32 v63, v60, v61
	s_waitcnt lgkmcnt(1)
	v_mov_b32_e32 v60, v48
	v_mov_b32_e32 v61, v50
	v_pk_fma_f32 v[60:61], v[148:149], v[88:89], v[60:61] op_sel_hi:[1,0,1]
	v_mov_b32_e32 v50, v49
	v_pk_mul_f32 v[56:57], v[56:57], v[60:61]
	v_mov_b32_e32 v125, v117
	v_cvt_pk_bf16_f32 v64, v56, v57
	s_waitcnt lgkmcnt(0)
	v_mov_b32_e32 v56, v52
	v_mov_b32_e32 v57, v54
	v_pk_fma_f32 v[56:57], v[146:147], v[88:89], v[56:57] op_sel_hi:[1,0,1]
	v_mov_b32_e32 v54, v53
	v_pk_mul_f32 v[56:57], v[58:59], v[56:57]
	v_lshl_add_u64 v[66:67], s[38:39], 0, v[124:125]
	v_cvt_pk_bf16_f32 v65, v56, v57
	v_pk_fma_f32 v[56:57], v[150:151], v[88:89], v[74:75] op_sel:[0,1,0]
	v_lshl_add_u64 v[68:69], s[40:41], 0, v[124:125]
	v_pk_mul_f32 v[42:43], v[42:43], v[56:57]
	s_nop 0
	v_cvt_pk_bf16_f32 v56, v42, v43
	v_pk_fma_f32 v[42:43], v[154:155], v[88:89], v[82:83] op_sel:[0,1,0]
	s_nop 0
	v_pk_mul_f32 v[38:39], v[38:39], v[42:43]
	s_nop 0
	v_cvt_pk_bf16_f32 v57, v38, v39
	v_pk_fma_f32 v[38:39], v[158:159], v[88:89], v[50:51] op_sel:[0,1,0]
	s_nop 0
	v_pk_mul_f32 v[22:23], v[22:23], v[38:39]
	s_nop 0
	v_cvt_pk_bf16_f32 v58, v22, v23
	v_pk_fma_f32 v[22:23], v[156:157], v[88:89], v[54:55] op_sel:[0,1,0]
	s_nop 0
	v_pk_mul_f32 v[22:23], v[30:31], v[22:23]
	s_nop 0
	v_cvt_pk_bf16_f32 v59, v22, v23
	v_add_co_u32_e32 v22, vcc, s72, v66
	s_nop 1
	v_addc_co_u32_e32 v23, vcc, 0, v67, vcc
	global_store_dwordx4 v[22:23], v[62:65], off
	v_add_co_u32_e32 v22, vcc, 0x2000, v68
	s_nop 1
	v_addc_co_u32_e32 v23, vcc, 0, v69, vcc
	s_andn2_b64 vcc, exec, s[42:43]
	global_store_dwordx4 v[22:23], v[56:59], off
	s_barrier
	s_cbranch_vccnz .LBB0_1019
	s_waitcnt vmcnt(0) lgkmcnt(0)
	s_barrier
	buffer_inv sc1
	s_waitcnt vmcnt(0)
	s_sub_i32 s4, s75, 0x80
	s_and_b32 s5, s4, 7
	s_lshr_b32 s4, s4, 7
	s_lshl_b32 s6, s4, 5
	s_lshl_b32 s7, s5, 13
	s_lshl_b32 s8, s6, 17
	s_lshl_b32 s9, s7, 1
	s_add_u32 s8, s8, s9
	s_add_u32 s10, s28, 0x27a00000
	s_addc_u32 s11, s29, 0
	s_add_u32 s10, s10, s8
	s_addc_u32 s11, s11, 0
	s_lshl_b32 s9, s7, 11
	s_lshl_b32 s14, s6, 1
	s_add_u32 s9, s9, s14
	s_add_u32 s14, s28, 0x7600000
	s_addc_u32 s15, s29, 0
	s_add_u32 s14, s14, s9
	s_addc_u32 s15, s15, 0
	v_and_b32_e32 v0, 63, v152
	v_lshrrev_b32_e32 v1, 6, v152
	v_lshrrev_b32_e32 v2, 3, v0
	v_and_b32_e32 v3, 7, v0
	v_lshlrev_b32_e32 v4, 17, v2
	v_lshl_add_u32 v4, v3, 4, v4
	v_lshlrev_b32_e32 v5, 13, v1
	v_mul_u32_u24_e32 v6, 0x88, v2
	v_add_u32_e32 v6, v6, v5
	v_lshl_add_u32 v6, v3, 4, v6
	v_and_b32_e32 v7, 3, v0
	v_lshrrev_b32_e32 v8, 2, v0
	v_mul_u32_u24_e32 v9, 0x440, v7
	v_add_u32_e32 v9, v9, v5
	v_lshl_add_u32 v9, v8, 1, v9
	v_lshlrev_b32_e32 v10, 11, v8
	v_lshl_add_u32 v10, v7, 4, v10
	v_lshlrev_b32_e32 v11, 7, v1
	v_add_u32_e32 v4, v4, v11
	v_lshlrev_b32_e32 v11, 17, v1
	v_add_u32_e32 v10, v10, v11
	v_add_u32_e32 v12, 0x0, v4
	v_add_u32_e32 v13, 0x100000, v4
	v_add_u32_e32 v14, 0x200000, v4
	v_add_u32_e32 v15, 0x300000, v4
	v_add_u32_e32 v16, 0x0, v10
	v_add_u32_e32 v17, 0x8000, v10
	v_add_u32_e32 v18, 0x10000, v10
	v_add_u32_e32 v19, 0x18000, v10
	global_load_dwordx4 v[32:35], v12, s[10:11]
	global_load_dwordx4 v[36:39], v13, s[10:11]
	global_load_dwordx4 v[40:43], v14, s[10:11]
	global_load_dwordx4 v[44:47], v15, s[10:11]
	v_add_u32_e32 v12, 0x400, v12
	v_add_u32_e32 v13, 0x400, v13
	v_add_u32_e32 v14, 0x400, v14
	v_add_u32_e32 v15, 0x400, v15
	s_mov_b32 s32, 0
; #define LAS __attribute__((address_space(3)))
; #define TP_LOAD(item_) do { const int c0_ = ((item_) & 15) * 64, t0_ = ((item_) >> 4) * 64; \
;         _Pragma("unroll") for (int j = 0; j < 8; ++j) nx[j] = *(const u32x4*)(Gc + (size_t)(c0_ + 8 * j + (lane >> 3)) * GLD + t0_ + 8 * (lane & 7)); } while (0)
; __device__ __forceinline__ void transpose_phase(LAS unsigned char* L, const Args& a) {
;     ...
;     if (gw < 16 * 1024) TP_LOAD(gw);
;     for (int item = gw; item < 16 * 1024; item += NGW) {
;         const int cblk = item & 15, tblk = item >> 4; const int c0 = cblk * 64, t0 = tblk * 64;
; #pragma unroll
;         for (int j = 0; j < 8; ++j) { const int c = 8 * j + (lane >> 3), ch = lane & 7; const u32x4 v = nx[j];
;             LAS unsigned* d = (LAS unsigned*)(T + c * 132 + ch * 16); d[0] = v.x; d[1] = v.y; d[2] = v.z; d[3] = v.w; }
;         if (item + NGW < 16 * 1024) TP_LOAD(item + NGW);
;         asm volatile("s_waitcnt lgkmcnt(0)" ::: "memory");
; #pragma unroll
;         for (int j = 0; j < 8; ++j) { const int t = 8 * j + (lane >> 3), ch = lane & 7; const LAS unsigned short* s = (const LAS unsigned short*)(T + (8 * ch) * 132 + 2 * t);
;             u32x4 o; o.x = (unsigned)s[0] | ((unsigned)s[66] << 16); o.y = (unsigned)s[132] | ((unsigned)s[198] << 16); o.z = (unsigned)s[264] | ((unsigned)s[330] << 16); o.w = (unsigned)s[396] | ((unsigned)s[462] << 16);
;             *(u32x4*)(GT + (size_t)(t0 + t) * 1024 + c0 + 8 * ch) = o; }
;         asm volatile("s_waitcnt lgkmcnt(0)" ::: "memory");
;     }
.Ltp_loop:
	global_load_dwordx4 v[48:51], v12, s[10:11]
	global_load_dwordx4 v[52:55], v13, s[10:11]
	global_load_dwordx4 v[56:59], v14, s[10:11]
	global_load_dwordx4 v[60:63], v15, s[10:11]
	v_add_u32_e32 v12, 0x400, v12
	v_add_u32_e32 v13, 0x400, v13
	v_add_u32_e32 v14, 0x400, v14
	v_add_u32_e32 v15, 0x400, v15
	s_waitcnt vmcnt(4)
	ds_write_b64 v6, v[32:33] offset:0
	ds_write_b64 v6, v[34:35] offset:8
	ds_write_b64 v6, v[36:37] offset:1088
	ds_write_b64 v6, v[38:39] offset:1096
	ds_write_b64 v6, v[40:41] offset:2176
	ds_write_b64 v6, v[42:43] offset:2184
	ds_write_b64 v6, v[44:45] offset:3264
	ds_write_b64 v6, v[46:47] offset:3272
	s_waitcnt lgkmcnt(0)
	ds_read_u16 v80, v9 offset:0
	ds_read_u16 v81, v9 offset:136
	ds_read_u16 v82, v9 offset:272
	ds_read_u16 v83, v9 offset:408
	ds_read_u16 v84, v9 offset:544
	ds_read_u16 v85, v9 offset:680
	ds_read_u16 v86, v9 offset:816
	ds_read_u16 v87, v9 offset:952
	ds_read_u16 v88, v9 offset:32
	ds_read_u16 v89, v9 offset:168
	ds_read_u16 v90, v9 offset:304
	ds_read_u16 v91, v9 offset:440
	ds_read_u16 v92, v9 offset:576
	ds_read_u16 v93, v9 offset:712
	ds_read_u16 v94, v9 offset:848
	ds_read_u16 v95, v9 offset:984
	ds_read_u16 v96, v9 offset:64
	ds_read_u16 v97, v9 offset:200
	ds_read_u16 v98, v9 offset:336
	ds_read_u16 v99, v9 offset:472
	ds_read_u16 v100, v9 offset:608
	ds_read_u16 v101, v9 offset:744
	ds_read_u16 v102, v9 offset:880
	ds_read_u16 v103, v9 offset:1016
	ds_read_u16 v104, v9 offset:96
	ds_read_u16 v105, v9 offset:232
	ds_read_u16 v106, v9 offset:368
	ds_read_u16 v107, v9 offset:504
	ds_read_u16 v108, v9 offset:640
	ds_read_u16 v109, v9 offset:776
	ds_read_u16 v110, v9 offset:912
	ds_read_u16 v111, v9 offset:1048
	s_waitcnt lgkmcnt(0)
	v_lshl_or_b32 v64, v81, 16, v80
	v_lshl_or_b32 v65, v83, 16, v82
	v_lshl_or_b32 v66, v85, 16, v84
	v_lshl_or_b32 v67, v87, 16, v86
	v_lshl_or_b32 v68, v89, 16, v88
	v_lshl_or_b32 v69, v91, 16, v90
	v_lshl_or_b32 v70, v93, 16, v92
	v_lshl_or_b32 v71, v95, 16, v94
	v_lshl_or_b32 v72, v97, 16, v96
	v_lshl_or_b32 v73, v99, 16, v98
	v_lshl_or_b32 v74, v101, 16, v100
	v_lshl_or_b32 v75, v103, 16, v102
	v_lshl_or_b32 v76, v105, 16, v104
	v_lshl_or_b32 v77, v107, 16, v106
	v_lshl_or_b32 v78, v109, 16, v108
	v_lshl_or_b32 v79, v111, 16, v110
	global_store_dwordx4 v16, v[64:67], s[14:15]
	global_store_dwordx4 v17, v[68:71], s[14:15]
	global_store_dwordx4 v18, v[72:75], s[14:15]
	global_store_dwordx4 v19, v[76:79], s[14:15]
	v_add_u32_e32 v16, 0x100000, v16
	v_add_u32_e32 v17, 0x100000, v17
	v_add_u32_e32 v18, 0x100000, v18
	v_add_u32_e32 v19, 0x100000, v19
	s_cmp_lt_u32 s32, 7
	s_cbranch_scc1 .Ltp_more
	v_subrev_u32_e32 v12, 0x400, v12
	v_subrev_u32_e32 v13, 0x400, v13
	v_subrev_u32_e32 v14, 0x400, v14
	v_subrev_u32_e32 v15, 0x400, v15
.Ltp_more:
	global_load_dwordx4 v[32:35], v12, s[10:11]
	global_load_dwordx4 v[36:39], v13, s[10:11]
	global_load_dwordx4 v[40:43], v14, s[10:11]
	global_load_dwordx4 v[44:47], v15, s[10:11]
	v_add_u32_e32 v12, 0x400, v12
	v_add_u32_e32 v13, 0x400, v13
	v_add_u32_e32 v14, 0x400, v14
	v_add_u32_e32 v15, 0x400, v15
	s_waitcnt vmcnt(8)
	ds_write_b64 v6, v[48:49] offset:0
	ds_write_b64 v6, v[50:51] offset:8
	ds_write_b64 v6, v[52:53] offset:1088
	ds_write_b64 v6, v[54:55] offset:1096
	ds_write_b64 v6, v[56:57] offset:2176
	ds_write_b64 v6, v[58:59] offset:2184
	ds_write_b64 v6, v[60:61] offset:3264
	ds_write_b64 v6, v[62:63] offset:3272
	s_waitcnt lgkmcnt(0)
	ds_read_u16 v80, v9 offset:0
	ds_read_u16 v81, v9 offset:136
	ds_read_u16 v82, v9 offset:272
	ds_read_u16 v83, v9 offset:408
	ds_read_u16 v84, v9 offset:544
	ds_read_u16 v85, v9 offset:680
	ds_read_u16 v86, v9 offset:816
	ds_read_u16 v87, v9 offset:952
	ds_read_u16 v88, v9 offset:32
	ds_read_u16 v89, v9 offset:168
	ds_read_u16 v90, v9 offset:304
	ds_read_u16 v91, v9 offset:440
	ds_read_u16 v92, v9 offset:576
	ds_read_u16 v93, v9 offset:712
	ds_read_u16 v94, v9 offset:848
	ds_read_u16 v95, v9 offset:984
	ds_read_u16 v96, v9 offset:64
	ds_read_u16 v97, v9 offset:200
	ds_read_u16 v98, v9 offset:336
	ds_read_u16 v99, v9 offset:472
	ds_read_u16 v100, v9 offset:608
	ds_read_u16 v101, v9 offset:744
	ds_read_u16 v102, v9 offset:880
	ds_read_u16 v103, v9 offset:1016
	ds_read_u16 v104, v9 offset:96
	ds_read_u16 v105, v9 offset:232
	ds_read_u16 v106, v9 offset:368
	ds_read_u16 v107, v9 offset:504
	ds_read_u16 v108, v9 offset:640
	ds_read_u16 v109, v9 offset:776
	ds_read_u16 v110, v9 offset:912
	ds_read_u16 v111, v9 offset:1048
	s_waitcnt lgkmcnt(0)
	v_lshl_or_b32 v64, v81, 16, v80
	v_lshl_or_b32 v65, v83, 16, v82
	v_lshl_or_b32 v66, v85, 16, v84
	v_lshl_or_b32 v67, v87, 16, v86
	v_lshl_or_b32 v68, v89, 16, v88
	v_lshl_or_b32 v69, v91, 16, v90
	v_lshl_or_b32 v70, v93, 16, v92
	v_lshl_or_b32 v71, v95, 16, v94
	v_lshl_or_b32 v72, v97, 16, v96
	v_lshl_or_b32 v73, v99, 16, v98
	v_lshl_or_b32 v74, v101, 16, v100
	v_lshl_or_b32 v75, v103, 16, v102
	v_lshl_or_b32 v76, v105, 16, v104
	v_lshl_or_b32 v77, v107, 16, v106
	v_lshl_or_b32 v78, v109, 16, v108
	v_lshl_or_b32 v79, v111, 16, v110
	global_store_dwordx4 v16, v[64:67], s[14:15]
	global_store_dwordx4 v17, v[68:71], s[14:15]
	global_store_dwordx4 v18, v[72:75], s[14:15]
	global_store_dwordx4 v19, v[76:79], s[14:15]
	v_add_u32_e32 v16, 0x100000, v16
	v_add_u32_e32 v17, 0x100000, v17
	v_add_u32_e32 v18, 0x100000, v18
	v_add_u32_e32 v19, 0x100000, v19
	s_add_i32 s32, s32, 1
	s_cmp_lt_u32 s32, 8
	s_cbranch_scc1 .Ltp_loop
	s_waitcnt vmcnt(0)
	v_lshrrev_b32_e32 v228, 6, v152

; #define LAS __attribute__((address_space(3)))
; #define TP_LOAD(item_) do { const int c0_ = ((item_) & 15) * 64, t0_ = ((item_) >> 4) * 64; \
;         _Pragma("unroll") for (int j = 0; j < 8; ++j) nx[j] = *(const u32x4*)(Gc + (size_t)(c0_ + 8 * j + (lane >> 3)) * GLD + t0_ + 8 * (lane & 7)); } while (0)
; __device__ __forceinline__ void transpose_phase(LAS unsigned char* L, const Args& a) {
;     const int tid = threadIdx.x, lane = tid & 63, w = tid >> 6; const int gw = blockIdx.x * 8 + w, NGW = gridDim.x * 8;
;     const bf16_t* Gc = (const bf16_t*)(a.ws + WS_G); bf16_t* GT = (bf16_t*)(a.ws + WS_GT);
;     LAS unsigned char* T = L + w * 16384;
;     u32x4 nx[8];
;     ...
;     if (gw < 16 * 1024) TP_LOAD(gw);
;     for (int item = gw; item < 16 * 1024; item += NGW) {
;         const int cblk = item & 15, tblk = item >> 4; const int c0 = cblk * 64, t0 = tblk * 64;
; #pragma unroll
;         for (int j = 0; j < 8; ++j) { const int c = 8 * j + (lane >> 3), ch = lane & 7; const u32x4 v = nx[j];
;             LAS unsigned* d = (LAS unsigned*)(T + c * 132 + ch * 16); d[0] = v.x; d[1] = v.y; d[2] = v.z; d[3] = v.w; }
;         if (item + NGW < 16 * 1024) TP_LOAD(item + NGW);
;         asm volatile("s_waitcnt lgkmcnt(0)" ::: "memory");
.LBB0_1137:
	s_cmp_lt_i32 s30, 13
	s_cselect_b64 s[4:5], -1, 0
	s_and_b64 s[4:5], s[4:5], s[0:1]
	s_andn2_b64 vcc, exec, s[4:5]
	s_branch .LBB0_1146
	v_lshl_add_u32 v38, s2, 3, v228
	s_movk_i32 s0, 0x4000
	v_cmp_gt_i32_e32 vcc, s0, v38
	s_and_saveexec_b64 s[6:7], vcc
	s_cbranch_execz .LBB0_1145
	v_lshlrev_b32_e32 v0, 3, v152
	s_lshl_b32 s12, s3, 3
	v_and_b32_e32 v44, 56, v0
	v_lshlrev_b32_e32 v0, 2, v38
	s_add_u32 s0, s28, 0x27a00000
	v_and_b32_e32 v0, 0xffffffc0, v0
	s_addc_u32 s1, s29, 0
	v_bfe_u32 v39, v152, 3, 3
	v_ashrrev_i32_e32 v1, 31, v0
	v_lshlrev_b32_e32 v2, 6, v38
	s_movk_i32 s13, 0x3c0
	v_lshlrev_b32_e32 v32, 1, v44
	v_mov_b32_e32 v33, 0
	v_lshl_add_u64 v[0:1], v[0:1], 1, s[0:1]
	v_and_or_b32 v2, v2, s13, v39
	v_lshl_add_u64 v[34:35], s[0:1], 0, v[32:33]
	v_lshl_add_u64 v[36:37], s[16:17], 0, v[32:33]
	v_lshl_add_u64 v[0:1], v[0:1], 0, v[32:33]
	v_lshlrev_b32_e32 v32, 17, v2
	v_lshl_add_u64 v[24:25], v[0:1], 0, v[32:33]
	s_mov_b32 s0, 0x100000
	v_add_co_u32_e32 v8, vcc, s0, v24
	s_mov_b32 s0, 0x200000
	s_nop 0
	v_addc_co_u32_e32 v9, vcc, 0, v25, vcc
	v_add_co_u32_e32 v16, vcc, s0, v24
	s_mov_b32 s0, 0x300000
	s_nop 0
	v_addc_co_u32_e32 v17, vcc, 0, v25, vcc
	v_add_co_u32_e32 v18, vcc, s0, v24
	s_mov_b32 s0, 0x400000
	s_nop 0
	v_addc_co_u32_e32 v19, vcc, 0, v25, vcc
	v_add_co_u32_e32 v26, vcc, s0, v24
	s_mov_b32 s0, 0x500000
	s_nop 0
	v_addc_co_u32_e32 v27, vcc, 0, v25, vcc
	v_add_co_u32_e32 v28, vcc, s0, v24
	s_mov_b32 s0, 0x600000
	s_nop 0
	v_addc_co_u32_e32 v29, vcc, 0, v25, vcc
	v_add_co_u32_e32 v40, vcc, s0, v24
	s_mov_b32 s0, 0x700000
	s_nop 0
	v_addc_co_u32_e32 v41, vcc, 0, v25, vcc
	v_add_co_u32_e32 v42, vcc, s0, v24
	global_load_dwordx4 v[0:3], v[24:25], off
	global_load_dwordx4 v[4:7], v[8:9], off
	s_nop 0
	global_load_dwordx4 v[8:11], v[16:17], off
	global_load_dwordx4 v[12:15], v[18:19], off
	s_nop 0
	global_load_dwordx4 v[16:19], v[26:27], off
	s_waitcnt lgkmcnt(0)
	global_load_dwordx4 v[20:23], v[28:29], off
	v_addc_co_u32_e32 v43, vcc, 0, v25, vcc
	global_load_dwordx4 v[24:27], v[40:41], off
	global_load_dwordx4 v[28:31], v[42:43], off
	v_lshlrev_b32_e32 v40, 4, v152
	v_lshl_add_u32 v32, v228, 14, 0
	v_and_b32_e32 v40, 0x70, v40
	s_movk_i32 s0, 0x84
	s_waitcnt vmcnt(0)
	v_add_u32_e32 v47, v32, v40
	v_mad_u32_u24 v32, v44, s0, v32
	v_or_b32_e32 v40, 8, v39
	v_or_b32_e32 v41, 16, v39
	v_or_b32_e32 v42, 24, v39
	v_or_b32_e32 v43, 32, v39
	v_or_b32_e32 v44, 40, v39
	v_or_b32_e32 v45, 48, v39
	v_or_b32_e32 v46, 56, v39
	v_lshlrev_b32_e32 v57, 6, v228
	v_lshlrev_b32_e32 v48, 1, v39
	v_mul_u32_u24_e32 v49, 0x84, v39
	v_lshlrev_b32_e32 v50, 1, v40
	v_lshlrev_b32_e32 v51, 1, v41
	v_lshlrev_b32_e32 v52, 1, v42
	v_lshlrev_b32_e32 v53, 1, v43
	v_lshlrev_b32_e32 v54, 1, v44
	v_lshlrev_b32_e32 v55, 1, v45
	v_lshlrev_b32_e32 v56, 1, v46
	v_lshl_add_u32 v58, s2, 9, v57
	v_lshlrev_b32_e32 v57, 2, v228
	s_lshl_b32 s14, s3, 9
	s_lshl_b32 s15, s3, 5
	v_lshl_add_u32 v59, s2, 5, v57
	s_mov_b64 s[8:9], 0
	v_add_u32_e32 v47, v47, v49
	s_movk_i32 s20, 0x3fff
	v_add_u32_e32 v48, v32, v48
	v_add_u32_e32 v49, v32, v50
	v_add_u32_e32 v50, v32, v51
	v_add_u32_e32 v51, v32, v52
	v_add_u32_e32 v52, v32, v53
	v_add_u32_e32 v53, v32, v54
	v_add_u32_e32 v54, v32, v55
	v_add_u32_e32 v55, v32, v56
	s_branch .LBB0_1141
